# conv_p done only by the 84 workgroups that own five (not six) K_A units
# speedup vs baseline: 1.0169x; 1.0169x over previous
; __device__ __forceinline__ int tid_() { int t = (int)threadIdx.x; asm volatile("" : "+v"(t)); return t & 511; }
; __device__ __forceinline__ int bid_() { int b = (int)blockIdx.x; asm volatile("" : "+s"(b)); return b; }
; __device__ __forceinline__ int gdim_() { int g = (int)gridDim.x; asm volatile("" : "+s"(g)); return g; }
; DI unsigned pk2(float lo, float hi) { const f32x2v v = {lo, hi}; const bf16x2v b = __builtin_convertvector(v, bf16x2v); return __builtin_bit_cast(unsigned, b); }
; DI void conv_p(const Params& P, int l) {
;     const int gt = bid_() * 512 + tid_(), NT = gdim_() * 512; bf16_t* PB = (bf16_t*)(P.ws + O_PBF);
; #pragma unroll 4
;     for (int i = gt; i < T * 64; i += NT) { const int row = i >> 6, c4 = (i & 63) * 4;
;         const float* src = row < TP ? P.in[I_PP] + ((size_t)l * TP + row) * 256 + c4 : P.in[I_PS] + ((size_t)l * 512 + (row - TP)) * 256 + c4;
;         const f32x4 v = *(const f32x4*)src; u32x2 w; w.x = pk2(v[0], v[1]); w.y = pk2(v[2], v[3]); *(u32x2*)(PB + (size_t)row * 256 + c4) = w; }
; DI void run_phase(const Params& P, int ph, LAS unsigned char* lds) {
;     ...
;     if (is_gemm) {
;         const bool mini = (g.nN == 4);
;         if (mini) g.nM = 64;
;         gemm_phase(lds, g, kind, l);
;         if (mini) mini_gemm(lds, g, kind, l);
;         if (kind == K_A) conv_p(fresh_params(), l);
.LBB0_891:
	s_and_b32 s2, 0xffff, s63
	s_cmp_lg_u32 s2, 1
	s_cbranch_scc1 .LBB0_922
	v_readlane_b32 s4, v254, 1
	v_readlane_b32 s5, v254, 2
	v_readlane_b32 s12, v254, 0
	v_readlane_b32 s17, v255, 34
	s_nop 0
	s_cmp_lg_u32 s17, 0x100
	s_cbranch_scc1 .Lconvp_all
	s_cmpk_lt_u32 s12, 0xac
	s_cbranch_scc1 .LBB0_922
	s_sub_u32 s12, s12, 0xac
	s_mov_b32 s17, 0x54
.Lconvp_all:
	v_mov_b32_e32 v0, v167
	s_lshl_b32 s10, s12, 9
	v_and_b32_e32 v0, 0x1ff, v0
	v_or_b32_e32 v8, s10, v0
	s_mov_b32 s2, 0x108000
	v_cmp_gt_i32_e32 vcc, s2, v8
	s_and_saveexec_b64 s[6:7], vcc
	s_cbranch_execz .LBB0_921
	s_lshl_b32 s2, s17, 9
	s_waitcnt lgkmcnt(0)
	v_cvt_f32_u32_e32 v1, s2
	s_load_dwordx2 s[8:9], s[4:5], 0x158
	v_rcp_iflag_f32_e32 v1, v1
	s_waitcnt lgkmcnt(0)
	s_add_u32 s8, s8, 0x11b20000
	s_addc_u32 s9, s9, 0
	v_mul_f32_e32 v1, 0x4f7ffffe, v1
	s_add_i32 s10, s10, s2
	v_cvt_u32_f32_e32 v1, v1
	v_or_b32_e32 v2, s10, v0
	s_mov_b32 s10, 0x108000
	v_cmp_gt_i32_e32 vcc, s10, v2
	v_max_i32_e32 v3, 0x108000, v2
	s_sub_i32 s10, 0, s2
	v_addc_co_u32_e64 v2, s[38:39], 0, v2, vcc
	v_sub_u32_e32 v2, v3, v2
	v_mul_lo_u32 v3, s10, v1
	v_mul_hi_u32 v3, v1, v3
	v_add_u32_e32 v1, v1, v3
	v_mul_hi_u32 v1, v2, v1
	v_mul_lo_u32 v3, v1, s2
	v_sub_u32_e32 v2, v2, v3
	v_add_u32_e32 v3, 1, v1
	v_cmp_le_u32_e64 s[38:39], s2, v2
	v_cndmask_b32_e64 v4, 1, 2, vcc
	s_and_b32 s11, s62, 0xff
	v_cndmask_b32_e64 v1, v1, v3, s[38:39]
	v_subrev_u32_e32 v3, s2, v2
	v_cndmask_b32_e64 v2, v2, v3, s[38:39]
	v_add_u32_e32 v3, 1, v1
	v_cmp_le_u32_e64 s[38:39], s2, v2
	s_lshl_b32 s3, s11, 9
	s_lshl_b32 s36, s11, 14
	v_cndmask_b32_e64 v1, v1, v3, s[38:39]
	v_add_u32_e32 v2, v4, v1
	v_and_b32_e32 v6, 3, v2
	v_cmp_ne_u32_e64 s[38:39], 0, v6
	s_and_saveexec_b64 s[10:11], s[38:39]
	s_cbranch_execz .LBB0_902
	v_lshlrev_b32_e32 v0, 2, v0
	v_lshl_or_b32 v7, s12, 11, v0
	s_lshl_b32 s16, s17, 11
	s_mov_b64 s[12:13], 0
	s_branch .LBB0_896
